# P0: read-once weight / pos loads marked nt (on top of P5 nt residual loads + sc1 out stores)
# baseline (speedup 1.0000x reference)
.LBB0_69:
	v_ashrrev_i32_e32 v14, 5, v12
	v_ashrrev_i32_e32 v15, 31, v14
	v_lshl_add_u64 v[14:15], v[14:15], 2, s[42:43]
	global_load_dword v4, v[14:15], off nt
	s_waitcnt vmcnt(0)
	v_cvt_f32_i32_e32 v4, v4
	v_mul_f32_e32 v13, v6, v4
	v_and_b32_e32 v14, 0x7fffffff, v13
	v_cmp_nlt_f32_e64 s[10:11], |v13|, s2
	s_and_saveexec_b64 s[12:13], s[10:11]
	s_xor_b64 s[22:23], exec, s[12:13]
	s_cbranch_execz .LBB0_71
	v_lshrrev_b32_e32 v4, 23, v14
	v_add_u32_e32 v4, 0xffffff88, v4
	v_cmp_lt_u32_e32 vcc, 63, v4
	s_nop 1
	v_cndmask_b32_e32 v15, 0, v9, vcc
	v_add_u32_e32 v4, v15, v4
	v_cmp_lt_u32_e64 s[10:11], 31, v4
	s_nop 1
	v_cndmask_b32_e64 v15, 0, v10, s[10:11]
	v_add_u32_e32 v4, v15, v4
	v_cmp_lt_u32_e64 s[12:13], 31, v4
	s_nop 1
	v_cndmask_b32_e64 v15, 0, v10, s[12:13]
	v_add_u32_e32 v15, v15, v4
	v_and_b32_e32 v4, 0x7fffff, v14
	v_or_b32_e32 v28, 0x800000, v4
	v_mad_u64_u32 v[16:17], s[14:15], v28, s3, 0
	v_mov_b32_e32 v4, v17
	v_mad_u64_u32 v[18:19], s[14:15], v28, s24, v[4:5]
	v_mov_b32_e32 v4, v19
	v_mad_u64_u32 v[20:21], s[14:15], v28, s25, v[4:5]
	v_mov_b32_e32 v4, v21
	v_mad_u64_u32 v[22:23], s[14:15], v28, s26, v[4:5]
	v_mov_b32_e32 v4, v23
	v_mad_u64_u32 v[24:25], s[14:15], v28, s27, v[4:5]
	v_mov_b32_e32 v4, v25
	v_mad_u64_u32 v[26:27], s[14:15], v28, s28, v[4:5]
	v_mov_b32_e32 v4, v27
	v_mad_u64_u32 v[28:29], s[14:15], v28, s29, v[4:5]
	v_cndmask_b32_e32 v17, v26, v22, vcc
	v_cndmask_b32_e32 v4, v28, v24, vcc
	v_cndmask_b32_e32 v21, v29, v26, vcc
	v_cndmask_b32_e64 v19, v4, v17, s[10:11]
	v_cndmask_b32_e64 v4, v21, v4, s[10:11]
	v_cndmask_b32_e32 v21, v24, v20, vcc
	v_cndmask_b32_e64 v17, v17, v21, s[10:11]
	v_cndmask_b32_e64 v4, v4, v19, s[12:13]
	v_cndmask_b32_e64 v19, v19, v17, s[12:13]
	v_sub_u32_e32 v23, 32, v15
	v_alignbit_b32 v24, v4, v19, v23
	v_cmp_eq_u32_e64 s[14:15], 0, v15
	v_cndmask_b32_e32 v16, v20, v16, vcc
	s_nop 0
	v_cndmask_b32_e64 v15, v24, v4, s[14:15]
	v_cndmask_b32_e32 v4, v22, v18, vcc
	v_cndmask_b32_e64 v18, v21, v4, s[10:11]
	v_cndmask_b32_e64 v17, v17, v18, s[12:13]
	v_alignbit_b32 v21, v19, v17, v23
	v_cndmask_b32_e64 v19, v21, v19, s[14:15]
	v_bfe_u32 v24, v15, 29, 1
	v_cndmask_b32_e64 v4, v4, v16, s[10:11]
	v_alignbit_b32 v21, v15, v19, 30
	v_sub_u32_e32 v25, 0, v24
	v_cndmask_b32_e64 v4, v18, v4, s[12:13]
	v_xor_b32_e32 v21, v21, v25
	v_alignbit_b32 v16, v17, v4, v23
	v_cndmask_b32_e64 v16, v16, v17, s[14:15]
	v_ffbh_u32_e32 v18, v21
	v_alignbit_b32 v17, v19, v16, 30
	v_min_u32_e32 v18, 32, v18
	v_alignbit_b32 v4, v16, v4, 30
	v_xor_b32_e32 v17, v17, v25
	v_sub_u32_e32 v19, 31, v18
	v_xor_b32_e32 v4, v4, v25
	v_alignbit_b32 v20, v21, v17, v19
	v_alignbit_b32 v4, v17, v4, v19
	v_alignbit_b32 v16, v20, v4, 9
	v_ffbh_u32_e32 v17, v16
	v_min_u32_e32 v17, 32, v17
	v_lshrrev_b32_e32 v22, 29, v15
	v_not_b32_e32 v19, v17
	v_alignbit_b32 v4, v16, v4, v19
	v_lshlrev_b32_e32 v16, 31, v22
	v_or_b32_e32 v19, 0x33000000, v16
	v_add_lshl_u32 v17, v17, v18, 23
	v_lshrrev_b32_e32 v4, 9, v4
	v_sub_u32_e32 v17, v19, v17
	v_or_b32_e32 v16, 0.5, v16
	v_lshlrev_b32_e32 v18, 23, v18
	v_or_b32_e32 v4, v17, v4
	v_lshrrev_b32_e32 v17, 9, v20
	v_sub_u32_e32 v16, v16, v18
	v_or_b32_e32 v16, v17, v16
	v_mul_f32_e32 v17, 0x3fc90fda, v16
	v_fma_f32 v18, v16, s30, -v17
	v_fmac_f32_e32 v18, 0x33a22168, v16
	v_fmac_f32_e32 v18, 0x3fc90fda, v4
	v_lshrrev_b32_e32 v15, 30, v15
	v_add_f32_e32 v4, v17, v18
	v_add_u32_e32 v15, v24, v15

.LBB0_100:
	s_or_saveexec_b64 s[10:11], s[10:11]
	v_mov_b32_e32 v8, 0
	v_mov_b32_e32 v9, 0
	v_mov_b32_e32 v10, 0
	v_mov_b32_e32 v11, 0
	s_xor_b64 exec, exec, s[10:11]
	s_cbranch_execz .LBB0_75
	s_mul_i32 s12, s20, 0xffcce000
	v_add_u32_e32 v10, s12, v6
	v_lshl_add_u64 v[8:9], v[2:3], 2, s[44:45]
	v_ashrrev_i32_e32 v11, 31, v10
	v_add_u32_e32 v14, 0x6640, v10
	v_lshl_add_u64 v[12:13], v[10:11], 2, v[8:9]
	v_ashrrev_i32_e32 v15, 31, v14
	v_add_u32_e32 v16, 0xcc80, v10
	v_add_u32_e32 v18, 0x132c0, v10
	v_add_u32_e32 v20, 0x19900, v10
	v_add_u32_e32 v22, 0x1ff40, v10
	v_add_u32_e32 v24, 0x26580, v10
	v_add_u32_e32 v10, 0x2cbc0, v10
	v_lshl_add_u64 v[14:15], v[14:15], 2, v[8:9]
	v_ashrrev_i32_e32 v17, 31, v16
	v_ashrrev_i32_e32 v19, 31, v18
	v_ashrrev_i32_e32 v21, 31, v20
	v_ashrrev_i32_e32 v23, 31, v22
	v_ashrrev_i32_e32 v25, 31, v24
	v_ashrrev_i32_e32 v11, 31, v10
	v_lshl_add_u64 v[16:17], v[16:17], 2, v[8:9]
	v_lshl_add_u64 v[18:19], v[18:19], 2, v[8:9]
	v_lshl_add_u64 v[20:21], v[20:21], 2, v[8:9]
	v_lshl_add_u64 v[22:23], v[22:23], 2, v[8:9]
	v_lshl_add_u64 v[24:25], v[24:25], 2, v[8:9]
	v_lshl_add_u64 v[26:27], v[10:11], 2, v[8:9]
	global_load_dword v2, v[12:13], off nt
	s_nop 0
	global_load_dword v12, v[14:15], off nt
	global_load_dword v13, v[16:17], off nt
	s_nop 0
	global_load_dword v14, v[18:19], off nt
	global_load_dword v8, v[20:21], off nt
	global_load_dword v9, v[22:23], off nt
	global_load_dword v10, v[24:25], off nt
	global_load_dword v11, v[26:27], off nt
	s_waitcnt vmcnt(7)
	ds_write_b32 v146, v2
	s_waitcnt vmcnt(6)
	ds_write_b32 v147, v12
	s_waitcnt vmcnt(5)
	ds_write_b32 v148, v13
	s_waitcnt vmcnt(4)
	ds_write_b32 v149, v14
	s_branch .LBB0_75

.LBB0_106:
	s_ashr_i32 s12, s19, 31
	s_lshr_b32 s12, s12, 30
	s_add_i32 s12, s19, s12
	s_ashr_i32 s20, s12, 2
	s_lshr_b32 s12, s20, 1
	s_mulk_i32 s12, 0x60
	s_bitcmp0_b32 s20, 0
	v_add_u32_e32 v6, s12, v154
	s_waitcnt vmcnt(1)
	v_add_u32_e32 v2, s12, v130
	v_cndmask_b32_e64 v6, -1, v6, s[4:5]
	s_cselect_b64 vcc, -1, 0
	v_cndmask_b32_e32 v2, v6, v2, vcc
	s_mul_i32 s14, s20, 0xfffd0000
	v_cmp_lt_i32_e64 s[12:13], -1, v2
	v_lshl_add_u64 v[6:7], v[2:3], 2, s[48:49]
	v_add_u32_e32 v8, s14, v10
	v_mov_b32_e32 v2, 0
	s_barrier
	s_and_saveexec_b64 s[14:15], s[12:13]
	s_cbranch_execz .LBB0_108
	v_ashrrev_i32_e32 v9, 31, v8
	v_lshl_add_u64 v[12:13], v[8:9], 2, v[6:7]
	global_load_dword v2, v[12:13], off nt
.LBB0_108:
	s_or_b64 exec, exec, s[14:15]
	s_lshl_b32 s14, s20, 8
	s_and_b64 vcc, exec, s[10:11]
	s_sub_i32 s16, 0, s14
	s_cbranch_vccnz .LBB0_110
	s_add_i32 s14, s16, s2
	v_add_u32_e32 v12, s14, v68
	v_ashrrev_i32_e32 v13, 31, v12
	v_lshl_add_u64 v[12:13], v[12:13], 2, s[46:47]
	global_load_dword v9, v[12:13], off nt
	s_waitcnt vmcnt(0)
	v_mul_f32_e32 v2, v2, v9
.LBB0_110:
	s_waitcnt vmcnt(0)
	ds_write_b32 v146, v2
	v_mov_b32_e32 v2, 0
	s_and_saveexec_b64 s[14:15], s[12:13]
	s_cbranch_execz .LBB0_112
	v_add_u32_e32 v12, 0x1800, v8
	v_ashrrev_i32_e32 v13, 31, v12
	v_lshl_add_u64 v[12:13], v[12:13], 2, v[6:7]
	global_load_dword v2, v[12:13], off nt
.LBB0_112:
	s_or_b64 exec, exec, s[14:15]
	s_and_b64 vcc, exec, s[10:11]
	s_add_i32 s14, s2, s16
	s_cbranch_vccnz .LBB0_114
	s_ashr_i32 s15, s14, 31
	v_lshl_add_u64 v[12:13], s[14:15], 0, v[68:69]
	v_lshl_add_u64 v[12:13], v[12:13], 2, s[46:47]
	global_load_dword v9, v[12:13], off offset:32 nt
	s_waitcnt vmcnt(0)
	v_mul_f32_e32 v2, v2, v9
.LBB0_114:
	s_waitcnt vmcnt(0)
	ds_write_b32 v147, v2
	v_mov_b32_e32 v2, 0
	s_and_saveexec_b64 s[16:17], s[12:13]
	s_cbranch_execz .LBB0_116
	v_add_u32_e32 v12, 0x3000, v8
	v_ashrrev_i32_e32 v13, 31, v12
	v_lshl_add_u64 v[12:13], v[12:13], 2, v[6:7]
	global_load_dword v2, v[12:13], off nt
.LBB0_116:
	s_or_b64 exec, exec, s[16:17]
	s_and_b64 vcc, exec, s[10:11]
	s_cbranch_vccnz .LBB0_118
	s_ashr_i32 s15, s14, 31
	v_lshl_add_u64 v[12:13], s[14:15], 0, v[68:69]
	v_lshl_add_u64 v[12:13], v[12:13], 2, s[46:47]
	global_load_dword v9, v[12:13], off offset:64 nt
	s_waitcnt vmcnt(0)
	v_mul_f32_e32 v2, v2, v9
.LBB0_118:
	s_waitcnt vmcnt(0)
	ds_write_b32 v148, v2
	v_mov_b32_e32 v2, 0
	s_and_saveexec_b64 s[16:17], s[12:13]
	s_cbranch_execz .LBB0_120
	v_add_u32_e32 v12, 0x4800, v8
	v_ashrrev_i32_e32 v13, 31, v12
	v_lshl_add_u64 v[12:13], v[12:13], 2, v[6:7]
	global_load_dword v2, v[12:13], off nt
.LBB0_120:
	s_or_b64 exec, exec, s[16:17]
	s_and_b64 vcc, exec, s[10:11]
	s_cbranch_vccnz .LBB0_122
	s_ashr_i32 s15, s14, 31
	v_lshl_add_u64 v[12:13], s[14:15], 0, v[68:69]
	v_lshl_add_u64 v[12:13], v[12:13], 2, s[46:47]
	global_load_dword v9, v[12:13], off offset:96 nt
	s_waitcnt vmcnt(0)
	v_mul_f32_e32 v2, v2, v9
.LBB0_122:
	s_waitcnt vmcnt(0)
	ds_write_b32 v149, v2
	v_mov_b32_e32 v2, 0
	s_and_saveexec_b64 s[16:17], s[12:13]
	s_cbranch_execz .LBB0_124
	v_add_u32_e32 v12, 0x6000, v8
	v_ashrrev_i32_e32 v13, 31, v12
	v_lshl_add_u64 v[12:13], v[12:13], 2, v[6:7]
	global_load_dword v2, v[12:13], off nt
.LBB0_124:
	s_or_b64 exec, exec, s[16:17]
	s_and_b64 vcc, exec, s[10:11]
	s_cbranch_vccnz .LBB0_126
	s_ashr_i32 s15, s14, 31
	v_lshl_add_u64 v[12:13], s[14:15], 0, v[68:69]
	v_lshl_add_u64 v[12:13], v[12:13], 2, s[46:47]
	global_load_dword v9, v[12:13], off offset:128 nt
	s_waitcnt vmcnt(0)
	v_mul_f32_e32 v2, v2, v9
.LBB0_126:
	s_waitcnt vmcnt(0)
	ds_write_b32 v150, v2
	v_mov_b32_e32 v2, 0
	s_and_saveexec_b64 s[16:17], s[12:13]
	s_cbranch_execz .LBB0_128
	v_add_u32_e32 v12, 0x7800, v8
	v_ashrrev_i32_e32 v13, 31, v12
	v_lshl_add_u64 v[12:13], v[12:13], 2, v[6:7]
	global_load_dword v2, v[12:13], off nt
.LBB0_128:
	s_or_b64 exec, exec, s[16:17]
	s_and_b64 vcc, exec, s[10:11]
	s_cbranch_vccnz .LBB0_130
	s_ashr_i32 s15, s14, 31
	v_lshl_add_u64 v[12:13], s[14:15], 0, v[68:69]
	v_lshl_add_u64 v[12:13], v[12:13], 2, s[46:47]
	global_load_dword v9, v[12:13], off offset:160 nt
	s_waitcnt vmcnt(0)
	v_mul_f32_e32 v2, v2, v9
.LBB0_130:
	s_waitcnt vmcnt(0)
	ds_write_b32 v151, v2
	v_mov_b32_e32 v2, 0
	s_and_saveexec_b64 s[16:17], s[12:13]
	s_cbranch_execz .LBB0_132
	v_add_u32_e32 v12, 0x9000, v8
	v_ashrrev_i32_e32 v13, 31, v12
	v_lshl_add_u64 v[12:13], v[12:13], 2, v[6:7]
	global_load_dword v2, v[12:13], off nt
.LBB0_132:
	s_or_b64 exec, exec, s[16:17]
	s_and_b64 vcc, exec, s[10:11]
	s_cbranch_vccnz .LBB0_134
	s_ashr_i32 s15, s14, 31
	v_lshl_add_u64 v[12:13], s[14:15], 0, v[68:69]
	v_lshl_add_u64 v[12:13], v[12:13], 2, s[46:47]
	global_load_dword v9, v[12:13], off offset:192 nt
	s_waitcnt vmcnt(0)
	v_mul_f32_e32 v2, v2, v9
.LBB0_134:
	s_waitcnt vmcnt(0)
	ds_write_b32 v152, v2
	v_mov_b32_e32 v2, 0
	s_and_saveexec_b64 s[16:17], s[12:13]
	s_cbranch_execz .LBB0_136
	v_add_u32_e32 v8, 0xa800, v8
	v_ashrrev_i32_e32 v9, 31, v8
	v_lshl_add_u64 v[6:7], v[8:9], 2, v[6:7]
	global_load_dword v2, v[6:7], off nt
.LBB0_136:
	s_or_b64 exec, exec, s[16:17]
	s_and_b64 vcc, exec, s[66:67]
	s_cbranch_vccz .LBB0_138
	s_ashr_i32 s15, s14, 31
	v_lshl_add_u64 v[6:7], s[14:15], 0, v[68:69]
	v_lshl_add_u64 v[6:7], v[6:7], 2, s[46:47]
	global_load_dword v6, v[6:7], off offset:224 nt
	s_waitcnt vmcnt(0)
	v_mul_f32_e32 v6, v2, v6
	s_cbranch_execnz .LBB0_105
	s_branch .LBB0_104

.LBB0_143:
	s_lshr_b32 s12, s16, 31
	s_add_i32 s12, s16, s12
	s_ashr_i32 s12, s12, 1
	s_lshl_b32 s17, s12, 6
	s_lshl_b32 s18, s12, 7
	s_cmp_gt_i32 s16, -2
	s_cselect_b64 s[14:15], -1, 0
	s_sub_i32 s12, s2, s18
	s_waitcnt vmcnt(1)
	v_or_b32_e32 v2, s17, v130
	v_add_u32_e32 v8, s12, v68
	s_cmp_lt_i32 s16, -1
	v_lshl_add_u64 v[6:7], v[2:3], 2, s[52:53]
	v_ashrrev_i32_e32 v9, 31, v8
	v_mov_b32_e32 v2, 0
	s_barrier
	s_cbranch_scc1 .LBB0_145
	v_lshlrev_b64 v[12:13], 12, v[8:9]
	v_lshl_add_u64 v[12:13], v[6:7], 0, v[12:13]
	global_load_dword v2, v[12:13], off nt
.LBB0_145:
	s_and_b64 vcc, exec, s[10:11]
	s_cbranch_vccnz .LBB0_147
	v_lshl_add_u64 v[12:13], v[8:9], 2, s[50:51]
	global_load_dword v9, v[12:13], off nt
	s_waitcnt vmcnt(0)
	v_mul_f32_e32 v2, v2, v9
.LBB0_147:
	s_waitcnt vmcnt(0)
	ds_write_b32 v146, v2
	v_cndmask_b32_e64 v2, 0, 1, s[14:15]
	v_cmp_ne_u32_e64 s[12:13], 1, v2
	s_andn2_b64 vcc, exec, s[14:15]
	v_mov_b32_e32 v2, 0
	s_cbranch_vccnz .LBB0_149
	v_add_u32_e32 v12, 8, v8
	v_ashrrev_i32_e32 v13, 31, v12
	v_lshlrev_b64 v[12:13], 12, v[12:13]
	v_lshl_add_u64 v[12:13], v[6:7], 0, v[12:13]
	global_load_dword v2, v[12:13], off nt
.LBB0_149:
	s_sub_i32 s14, 0, s18
	s_and_b64 vcc, exec, s[10:11]
	s_add_i32 s14, s2, s14
	s_cbranch_vccnz .LBB0_151
	s_ashr_i32 s15, s14, 31
	v_lshl_add_u64 v[12:13], s[14:15], 0, v[68:69]
	v_lshl_add_u64 v[12:13], v[12:13], 2, s[50:51]
	global_load_dword v9, v[12:13], off offset:32 nt
	s_waitcnt vmcnt(0)
	v_mul_f32_e32 v2, v2, v9
.LBB0_151:
	s_waitcnt vmcnt(0)
	ds_write_b32 v147, v2
	s_and_b64 vcc, exec, s[12:13]
	v_mov_b32_e32 v2, 0
	s_cbranch_vccnz .LBB0_153
	v_add_u32_e32 v12, 16, v8
	v_ashrrev_i32_e32 v13, 31, v12
	v_lshlrev_b64 v[12:13], 12, v[12:13]
	v_lshl_add_u64 v[12:13], v[6:7], 0, v[12:13]
	global_load_dword v2, v[12:13], off nt
.LBB0_153:
	s_and_b64 vcc, exec, s[10:11]
	s_cbranch_vccnz .LBB0_155
	s_ashr_i32 s15, s14, 31
	v_lshl_add_u64 v[12:13], s[14:15], 0, v[68:69]
	v_lshl_add_u64 v[12:13], v[12:13], 2, s[50:51]
	global_load_dword v9, v[12:13], off offset:64 nt
	s_waitcnt vmcnt(0)
	v_mul_f32_e32 v2, v2, v9
.LBB0_155:
	s_waitcnt vmcnt(0)
	ds_write_b32 v148, v2
	s_and_b64 vcc, exec, s[12:13]
	v_mov_b32_e32 v2, 0
	s_cbranch_vccnz .LBB0_157
	v_add_u32_e32 v12, 24, v8
	v_ashrrev_i32_e32 v13, 31, v12
	v_lshlrev_b64 v[12:13], 12, v[12:13]
	v_lshl_add_u64 v[12:13], v[6:7], 0, v[12:13]
	global_load_dword v2, v[12:13], off nt
.LBB0_157:
	s_and_b64 vcc, exec, s[10:11]
	s_cbranch_vccnz .LBB0_159
	s_ashr_i32 s15, s14, 31
	v_lshl_add_u64 v[12:13], s[14:15], 0, v[68:69]
	v_lshl_add_u64 v[12:13], v[12:13], 2, s[50:51]
	global_load_dword v9, v[12:13], off offset:96 nt
	s_waitcnt vmcnt(0)
	v_mul_f32_e32 v2, v2, v9
.LBB0_159:
	s_waitcnt vmcnt(0)
	ds_write_b32 v149, v2
	s_and_b64 vcc, exec, s[12:13]
	v_mov_b32_e32 v2, 0
	s_cbranch_vccnz .LBB0_161
	v_add_u32_e32 v12, 32, v8
	v_ashrrev_i32_e32 v13, 31, v12
	v_lshlrev_b64 v[12:13], 12, v[12:13]
	v_lshl_add_u64 v[12:13], v[6:7], 0, v[12:13]
	global_load_dword v2, v[12:13], off nt
.LBB0_161:
	s_and_b64 vcc, exec, s[10:11]
	s_cbranch_vccnz .LBB0_163
	s_ashr_i32 s15, s14, 31
	v_lshl_add_u64 v[12:13], s[14:15], 0, v[68:69]
	v_lshl_add_u64 v[12:13], v[12:13], 2, s[50:51]
	global_load_dword v9, v[12:13], off offset:128 nt
	s_waitcnt vmcnt(0)
	v_mul_f32_e32 v2, v2, v9
.LBB0_163:
	s_waitcnt vmcnt(0)
	ds_write_b32 v150, v2
	s_and_b64 vcc, exec, s[12:13]
	v_mov_b32_e32 v2, 0
	s_cbranch_vccnz .LBB0_165
	v_add_u32_e32 v12, 40, v8
	v_ashrrev_i32_e32 v13, 31, v12
	v_lshlrev_b64 v[12:13], 12, v[12:13]
	v_lshl_add_u64 v[12:13], v[6:7], 0, v[12:13]
	global_load_dword v2, v[12:13], off nt
.LBB0_165:
	s_and_b64 vcc, exec, s[10:11]
	s_cbranch_vccnz .LBB0_167
	s_ashr_i32 s15, s14, 31
	v_lshl_add_u64 v[12:13], s[14:15], 0, v[68:69]
	v_lshl_add_u64 v[12:13], v[12:13], 2, s[50:51]
	global_load_dword v9, v[12:13], off offset:160 nt
	s_waitcnt vmcnt(0)
	v_mul_f32_e32 v2, v2, v9
.LBB0_167:
	s_waitcnt vmcnt(0)
	ds_write_b32 v151, v2
	s_and_b64 vcc, exec, s[12:13]
	v_mov_b32_e32 v2, 0
	s_cbranch_vccnz .LBB0_169
	v_add_u32_e32 v12, 48, v8
	v_ashrrev_i32_e32 v13, 31, v12
	v_lshlrev_b64 v[12:13], 12, v[12:13]
	v_lshl_add_u64 v[12:13], v[6:7], 0, v[12:13]
	global_load_dword v2, v[12:13], off nt
.LBB0_169:
	s_and_b64 vcc, exec, s[10:11]
	s_cbranch_vccnz .LBB0_171
	s_ashr_i32 s15, s14, 31
	v_lshl_add_u64 v[12:13], s[14:15], 0, v[68:69]
	v_lshl_add_u64 v[12:13], v[12:13], 2, s[50:51]
	global_load_dword v9, v[12:13], off offset:192 nt
	s_waitcnt vmcnt(0)
	v_mul_f32_e32 v2, v2, v9
.LBB0_171:
	s_waitcnt vmcnt(0)
	ds_write_b32 v152, v2
	s_and_b64 vcc, exec, s[12:13]
	v_mov_b32_e32 v2, 0
	s_cbranch_vccnz .LBB0_173
	v_add_u32_e32 v8, 56, v8
	v_ashrrev_i32_e32 v9, 31, v8
	v_lshlrev_b64 v[8:9], 12, v[8:9]
	v_lshl_add_u64 v[6:7], v[6:7], 0, v[8:9]
	global_load_dword v2, v[6:7], off nt
.LBB0_173:
	s_and_b64 vcc, exec, s[64:65]
	s_cbranch_vccz .LBB0_175
	s_ashr_i32 s15, s14, 31
	v_lshl_add_u64 v[6:7], s[14:15], 0, v[68:69]
	v_lshl_add_u64 v[6:7], v[6:7], 2, s[50:51]
	global_load_dword v6, v[6:7], off offset:224 nt
	s_waitcnt vmcnt(0)
	v_mul_f32_e32 v6, v2, v6
	s_cbranch_execnz .LBB0_142
	s_branch .LBB0_141

.LBB0_181:
	s_ashr_i32 s13, s12, 31
	s_lshr_b32 s13, s13, 28
	s_add_i32 s13, s12, s13
	s_ashr_i32 s14, s13, 4
	s_lshl_b32 s13, s14, 6
	s_lshl_b32 s14, s14, 10
	s_sub_i32 s14, 0, s14
	s_waitcnt vmcnt(1)
	v_mov_b32_e32 v2, 0
	s_andn2_b64 vcc, exec, s[10:11]
	v_mov_b32_e32 v7, 0
	v_mov_b32_e32 v8, 0
	v_mov_b32_e32 v9, 0
	s_cbranch_vccnz .LBB0_178
	s_add_i32 s10, s14, s2
	v_add_u32_e32 v10, s10, v68
	v_ashrrev_i32_e32 v11, 31, v10
	v_add_u32_e32 v14, 8, v10
	v_or_b32_e32 v2, s13, v130
	v_lshlrev_b64 v[12:13], 12, v[10:11]
	v_ashrrev_i32_e32 v15, 31, v14
	v_add_u32_e32 v16, 16, v10
	v_add_u32_e32 v18, 24, v10
	v_add_u32_e32 v20, 32, v10
	v_add_u32_e32 v22, 40, v10
	v_add_u32_e32 v24, 48, v10
	v_add_u32_e32 v10, 56, v10
	v_lshl_add_u64 v[8:9], v[2:3], 2, s[54:55]
	v_lshlrev_b64 v[14:15], 12, v[14:15]
	v_ashrrev_i32_e32 v17, 31, v16
	v_ashrrev_i32_e32 v19, 31, v18
	v_ashrrev_i32_e32 v21, 31, v20
	v_ashrrev_i32_e32 v23, 31, v22
	v_ashrrev_i32_e32 v25, 31, v24
	v_ashrrev_i32_e32 v11, 31, v10
	v_lshl_add_u64 v[12:13], v[8:9], 0, v[12:13]
	v_lshl_add_u64 v[14:15], v[8:9], 0, v[14:15]
	v_lshlrev_b64 v[16:17], 12, v[16:17]
	v_lshlrev_b64 v[18:19], 12, v[18:19]
	v_lshlrev_b64 v[20:21], 12, v[20:21]
	v_lshlrev_b64 v[22:23], 12, v[22:23]
	v_lshlrev_b64 v[24:25], 12, v[24:25]
	v_lshlrev_b64 v[10:11], 12, v[10:11]
	v_lshl_add_u64 v[16:17], v[8:9], 0, v[16:17]
	v_lshl_add_u64 v[18:19], v[8:9], 0, v[18:19]
	v_lshl_add_u64 v[20:21], v[8:9], 0, v[20:21]
	v_lshl_add_u64 v[22:23], v[8:9], 0, v[22:23]
	v_lshl_add_u64 v[24:25], v[8:9], 0, v[24:25]
	v_lshl_add_u64 v[10:11], v[8:9], 0, v[10:11]
	global_load_dword v12, v[12:13], off nt
	s_nop 0
	global_load_dword v13, v[14:15], off nt
	s_nop 0
	global_load_dword v14, v[16:17], off nt
	global_load_dword v15, v[18:19], off nt
	global_load_dword v2, v[20:21], off nt
	global_load_dword v7, v[22:23], off nt
	global_load_dword v8, v[24:25], off nt
	global_load_dword v9, v[10:11], off nt
	s_waitcnt vmcnt(7)
	ds_write_b32 v146, v12
	s_waitcnt vmcnt(6)
	ds_write_b32 v147, v13
	s_waitcnt vmcnt(5)
	ds_write_b32 v148, v14
	s_waitcnt vmcnt(4)
	ds_write_b32 v149, v15
	s_branch .LBB0_178

.LBB0_293:
	s_ashr_i32 s13, s12, 31
	s_lshr_b32 s13, s13, 28
	s_add_i32 s13, s12, s13
	s_ashr_i32 s14, s13, 4
	s_lshl_b32 s13, s14, 6
	s_lshl_b32 s14, s14, 10
	s_sub_i32 s14, 0, s14
	s_waitcnt vmcnt(1)
	v_mov_b32_e32 v2, 0
	s_andn2_b64 vcc, exec, s[10:11]
	v_mov_b32_e32 v7, 0
	v_mov_b32_e32 v8, 0
	v_mov_b32_e32 v9, 0
	s_cbranch_vccnz .LBB0_290
	s_add_i32 s10, s14, s2
	v_add_u32_e32 v10, s10, v68
	v_ashrrev_i32_e32 v11, 31, v10
	v_or_b32_e32 v2, s13, v130
	v_lshlrev_b64 v[12:13], 12, v[10:11]
	v_add_u32_e32 v14, 8, v10
	v_add_u32_e32 v16, 16, v10
	v_add_u32_e32 v18, 24, v10
	v_add_u32_e32 v20, 32, v10
	v_add_u32_e32 v22, 40, v10
	v_add_u32_e32 v24, 48, v10
	v_add_u32_e32 v10, 56, v10
	v_lshl_add_u64 v[8:9], v[2:3], 2, s[54:55]
	v_ashrrev_i32_e32 v15, 31, v14
	v_ashrrev_i32_e32 v17, 31, v16
	v_ashrrev_i32_e32 v19, 31, v18
	v_ashrrev_i32_e32 v21, 31, v20
	v_ashrrev_i32_e32 v23, 31, v22
	v_ashrrev_i32_e32 v25, 31, v24
	v_ashrrev_i32_e32 v11, 31, v10
	v_lshl_add_u64 v[12:13], v[8:9], 0, v[12:13]
	v_lshlrev_b64 v[14:15], 12, v[14:15]
	v_lshlrev_b64 v[16:17], 12, v[16:17]
	v_lshlrev_b64 v[18:19], 12, v[18:19]
	v_lshlrev_b64 v[20:21], 12, v[20:21]
	v_lshlrev_b64 v[22:23], 12, v[22:23]
	v_lshlrev_b64 v[24:25], 12, v[24:25]
	v_lshlrev_b64 v[10:11], 12, v[10:11]
	v_lshl_add_u64 v[14:15], v[8:9], 0, v[14:15]
	v_lshl_add_u64 v[16:17], v[8:9], 0, v[16:17]
	v_lshl_add_u64 v[18:19], v[8:9], 0, v[18:19]
	v_lshl_add_u64 v[20:21], v[8:9], 0, v[20:21]
	v_lshl_add_u64 v[22:23], v[8:9], 0, v[22:23]
	v_lshl_add_u64 v[24:25], v[8:9], 0, v[24:25]
	v_lshl_add_u64 v[10:11], v[8:9], 0, v[10:11]
	global_load_dword v26, v[12:13], off nt
	global_load_dword v27, v[14:15], off nt
	global_load_dword v28, v[16:17], off nt
	global_load_dword v29, v[18:19], off nt
	global_load_dword v2, v[20:21], off nt
	global_load_dword v7, v[22:23], off nt
	global_load_dword v8, v[24:25], off nt
	global_load_dword v9, v[10:11], off nt
	s_waitcnt vmcnt(7)
	ds_write_b32 v146, v26
	s_waitcnt vmcnt(6)
	ds_write_b32 v147, v27
	s_waitcnt vmcnt(5)
	ds_write_b32 v148, v28
	s_waitcnt vmcnt(4)
	ds_write_b32 v149, v29
	s_branch .LBB0_290

.LBB0_361:
	v_ashrrev_i32_e32 v12, 5, v66
	v_ashrrev_i32_e32 v13, 31, v12
	v_lshl_add_u64 v[12:13], v[12:13], 2, s[42:43]
	global_load_dword v4, v[12:13], off nt
	s_waitcnt vmcnt(0)
	v_cvt_f32_i32_e32 v4, v4
	v_mul_f32_e32 v12, v6, v4
	v_and_b32_e32 v13, 0x7fffffff, v12
	v_cmp_nlt_f32_e64 s[6:7], |v12|, s2
	s_and_saveexec_b64 s[8:9], s[6:7]
	s_xor_b64 s[18:19], exec, s[8:9]
	s_cbranch_execz .LBB0_363
	v_lshrrev_b32_e32 v4, 23, v13
	v_add_u32_e32 v4, 0xffffff88, v4
	v_cmp_lt_u32_e32 vcc, 63, v4
	s_nop 1
	v_cndmask_b32_e32 v14, 0, v9, vcc
	v_add_u32_e32 v4, v14, v4
	v_cmp_lt_u32_e64 s[6:7], 31, v4
	s_nop 1
	v_cndmask_b32_e64 v14, 0, v10, s[6:7]
	v_add_u32_e32 v4, v14, v4
	v_cmp_lt_u32_e64 s[8:9], 31, v4
	s_nop 1
	v_cndmask_b32_e64 v14, 0, v10, s[8:9]
	v_add_u32_e32 v28, v14, v4
	v_and_b32_e32 v4, 0x7fffff, v13
	v_or_b32_e32 v26, 0x800000, v4
	v_mad_u64_u32 v[14:15], s[10:11], v26, s3, 0
	v_mov_b32_e32 v4, v15
	v_mad_u64_u32 v[16:17], s[10:11], v26, s20, v[4:5]
	v_mov_b32_e32 v4, v17
	v_mad_u64_u32 v[18:19], s[10:11], v26, s21, v[4:5]
	v_mov_b32_e32 v4, v19
	v_mad_u64_u32 v[20:21], s[10:11], v26, s22, v[4:5]
	v_mov_b32_e32 v4, v21
	v_mad_u64_u32 v[22:23], s[10:11], v26, s23, v[4:5]
	v_mov_b32_e32 v4, v23
	v_mad_u64_u32 v[24:25], s[10:11], v26, s24, v[4:5]
	v_mov_b32_e32 v4, v25
	v_mad_u64_u32 v[26:27], s[10:11], v26, s25, v[4:5]
	v_cndmask_b32_e32 v15, v24, v20, vcc
	v_cndmask_b32_e32 v4, v26, v22, vcc
	v_cndmask_b32_e32 v19, v27, v24, vcc
	v_cndmask_b32_e64 v17, v4, v15, s[6:7]
	v_cndmask_b32_e64 v4, v19, v4, s[6:7]
	v_cndmask_b32_e32 v19, v22, v18, vcc
	v_cndmask_b32_e64 v15, v15, v19, s[6:7]
	v_cndmask_b32_e64 v4, v4, v17, s[8:9]
	v_cndmask_b32_e64 v17, v17, v15, s[8:9]
	v_sub_u32_e32 v21, 32, v28
	v_alignbit_b32 v22, v4, v17, v21
	v_cmp_eq_u32_e64 s[10:11], 0, v28
	v_cndmask_b32_e32 v14, v18, v14, vcc
	s_nop 0
	v_cndmask_b32_e64 v22, v22, v4, s[10:11]
	v_cndmask_b32_e32 v4, v20, v16, vcc
	v_cndmask_b32_e64 v16, v19, v4, s[6:7]
	v_cndmask_b32_e64 v15, v15, v16, s[8:9]
	v_alignbit_b32 v19, v17, v15, v21
	v_cndmask_b32_e64 v17, v19, v17, s[10:11]
	v_bfe_u32 v23, v22, 29, 1
	v_cndmask_b32_e64 v4, v4, v14, s[6:7]
	v_alignbit_b32 v19, v22, v17, 30
	v_sub_u32_e32 v24, 0, v23
	v_cndmask_b32_e64 v4, v16, v4, s[8:9]
	v_xor_b32_e32 v19, v19, v24
	v_alignbit_b32 v14, v15, v4, v21
	v_cndmask_b32_e64 v14, v14, v15, s[10:11]
	v_ffbh_u32_e32 v16, v19
	v_alignbit_b32 v15, v17, v14, 30
	v_min_u32_e32 v16, 32, v16
	v_alignbit_b32 v4, v14, v4, 30
	v_xor_b32_e32 v15, v15, v24
	v_sub_u32_e32 v17, 31, v16
	v_xor_b32_e32 v4, v4, v24
	v_alignbit_b32 v18, v19, v15, v17
	v_alignbit_b32 v4, v15, v4, v17
	v_alignbit_b32 v14, v18, v4, 9
	v_ffbh_u32_e32 v15, v14
	v_min_u32_e32 v15, 32, v15
	v_lshrrev_b32_e32 v20, 29, v22
	v_not_b32_e32 v17, v15
	v_alignbit_b32 v4, v14, v4, v17
	v_lshlrev_b32_e32 v14, 31, v20
	v_or_b32_e32 v17, 0x33000000, v14
	v_add_lshl_u32 v15, v15, v16, 23
	v_lshrrev_b32_e32 v4, 9, v4
	v_sub_u32_e32 v15, v17, v15
	v_or_b32_e32 v14, 0.5, v14
	v_lshlrev_b32_e32 v16, 23, v16
	v_or_b32_e32 v4, v15, v4
	v_lshrrev_b32_e32 v15, 9, v18
	v_sub_u32_e32 v14, v14, v16
	v_or_b32_e32 v14, v15, v14
	v_mul_f32_e32 v15, 0x3fc90fda, v14
	v_fma_f32 v16, v14, s26, -v15
	v_fmac_f32_e32 v16, 0x33a22168, v14
	v_fmac_f32_e32 v16, 0x3fc90fda, v4
	v_lshrrev_b32_e32 v14, 30, v22
	v_add_f32_e32 v4, v15, v16
	v_add_u32_e32 v14, v23, v14
